# v75 + attention K/V tile loads addressed SGPR base + 32-bit lane offset, pointer advance scalar (14 address VALU per tile removed)
# speedup vs baseline: 1.0117x; 1.0044x over previous
; DI CP* kparams() { CP* kp = (CP*)__builtin_amdgcn_kernarg_segment_ptr(); asm volatile("" : "+s"(kp)); return kp; }
; DI int lane_id() { int l = __builtin_amdgcn_mbcnt_hi(-1, __builtin_amdgcn_mbcnt_lo(-1, 0)); asm volatile("" : "+v"(l)); return l; }
; #define A_LOAD(kt) do { const size_t ko = (size_t)(kt) * 64; st0 = *(const u32x4*)(kn_src + ko * 2048); st1 = *(const u32x4*)(kn_src + (ko + 32) * 2048); \
;         st2 = *(const u32x4*)(kr_src + ko * 64); st3 = *(const u32x4*)(v_src + ko); st4 = *(const u32x4*)(v_src + ko + (size_t)64 * 8192); } while (0)
; DI void attn_unit(LAS unsigned char* lds, int wid, int b, int h, int qb) {
;     CP& p = *kparams();
;     const int lane = lane_id(), tid = wid * 64 + lane, n = lane & 31, g = lane >> 5;
;     const int q0 = qb * 256 + wid * 32, cq = q0 >> 6, nkt = 4 * qb + 4;
;     const size_t tokq = (size_t)b * SEQ + q0 + n;
;     const bf16_t* Q = WSB(OFF_Q); const bf16_t* KN = WSB(OFF_KN); const bf16_t* KR = WSB(OFF_KR); const bf16_t* VT = WSB(OFF_VT2);
;     bf16x8 qf[12];
; #pragma unroll
;     for (int ks = 0; ks < 12; ++ks) qf[ks] = *(const bf16x8*)(Q + tokq * 3072 + h * 192 + ks * 16 + g * 8);
;     f32x16 o[4];
; #pragma unroll
;     for (int dt = 0; dt < 4; ++dt)
; #pragma unroll
;         for (int i = 0; i < 16; ++i) o[dt][i] = 0.f;
;     float mrow = -__builtin_inff(), lrow = 0.f;
;     const int krow = tid >> 4, kc16 = tid & 15, rrow = tid >> 3, rc8 = tid & 7;
;     const bf16_t* kn_src = KN + ((size_t)b * SEQ + krow) * 2048 + h * 128 + kc16 * 8;
;     const bf16_t* kr_src = KR + ((size_t)b * SEQ + rrow) * 64 + rc8 * 8;
;     const bf16_t* v_src = VT + ((size_t)h * 128 + rrow) * 8192 + (size_t)b * SEQ + rc8 * 8;
;     const int kn_dst = krow * KROW + kc16 * 16, kr_dst = rrow * KROW + 256 + rc8 * 16, v_dst = KBYTES + rrow * VROW + rc8 * 16;
;     u32x4 st0, st1, st2, st3, st4;
;     ...
;     A_LOAD(0); A_WRITE(0); __syncthreads();
.LBB0_1078:
	s_lshl_b32 s4, s55, 2
	s_and_b32 s4, s4, 28
	s_ashr_i32 s59, s55, 6
	s_mov_b64 s[16:17], s[0:1]
	v_mov_b32_e32 v183, v201
	s_add_i32 s4, s4, s59
	s_bfe_u32 s56, s55, 0x30003
	s_load_dwordx2 s[24:25], s[16:17], 0xa8
	s_ashr_i32 s22, s4, 4
	s_and_b32 s20, s4, 15
	s_xor_b32 s4, s56, 15
	s_lshl_b32 s18, s4, 8
	s_ashr_i32 s23, s22, 31
	s_lshr_b32 s57, s55, 3
	s_add_i32 s21, s18, s29
	s_lshl_b32 s61, s4, 2
	s_lshl_b64 s[16:17], s[22:23], 12
	v_and_b32_e32 v197, 31, v183
	s_add_u32 s26, s16, s21
	v_or_b32_e32 v0, s26, v197
	s_waitcnt lgkmcnt(0)
	v_mov_b64_e32 v[2:3], s[24:25]
	v_mad_u64_u32 v[2:3], s[18:19], v0, s37, v[2:3]
	v_add_u32_e32 v0, s28, v183
	v_ashrrev_i32_e32 v26, 3, v0
	v_ashrrev_i32_e32 v27, 31, v26
	s_addc_u32 s27, s17, 0
	s_mul_i32 s58, s20, 0xc0
	v_ashrrev_i32_e32 v24, 4, v0
	v_lshl_add_u64 v[4:5], s[16:17], 0, v[26:27]
	v_mad_i32_i24 v3, s27, v200, v3
	s_lshl_b32 s4, s58, 1
	v_ashrrev_i32_e32 v25, 31, v24
	v_lshlrev_b64 v[4:5], 7, v[4:5]
	v_lshlrev_b32_e32 v6, 4, v183
	v_lshl_add_u64 v[22:23], v[2:3], 0, s[4:5]
	v_lshl_add_u64 v[2:3], s[16:17], 0, v[24:25]
	s_lshl_b32 s4, s20, 7
	v_lshl_add_u64 v[4:5], s[24:25], 0, v[4:5]
	v_and_b32_e32 v28, 0x70, v6
	v_mov_b32_e32 v29, v1
	v_lshlrev_b64 v[2:3], 12, v[2:3]
	v_lshl_add_u64 v[10:11], v[4:5], 0, v[28:29]
	v_lshl_add_u64 v[4:5], v[26:27], 0, s[4:5]
	v_and_b32_e32 v32, 15, v183
	v_lshl_add_u64 v[2:3], s[24:25], 0, v[2:3]
	s_lshl_b32 s18, s20, 8
	s_mov_b32 s19, s5
	v_lshlrev_b64 v[4:5], 14, v[4:5]
	v_lshl_add_u64 v[2:3], v[2:3], 0, s[18:19]
	v_lshlrev_b32_e32 v0, 4, v32
	v_lshl_add_u64 v[4:5], s[24:25], 0, v[4:5]
	s_lshl_b64 s[18:19], s[22:23], 13
	v_lshl_add_u64 v[2:3], v[2:3], 0, v[0:1]
	v_lshl_add_u64 v[4:5], v[4:5], 0, s[18:19]
	v_lshl_add_u64 v[18:19], v[4:5], 0, v[28:29]
	v_add_co_u32_e32 v4, vcc, s40, v2
	v_ashrrev_i32_e32 v29, 5, v183
	s_nop 0
	v_addc_co_u32_e32 v5, vcc, 0, v3, vcc
	v_add_co_u32_e32 v6, vcc, s41, v2
	v_lshlrev_b32_e32 v184, 3, v29
	s_nop 0
	v_addc_co_u32_e32 v7, vcc, 0, v3, vcc
	v_add_co_u32_e32 v10, vcc, s42, v10
	v_ashrrev_i32_e32 v185, 31, v184
	s_nop 0
	v_addc_co_u32_e32 v11, vcc, 0, v11, vcc
	v_add_co_u32_e32 v14, vcc, s43, v18
	v_lshl_add_u64 v[22:23], v[184:185], 1, v[22:23]
	s_nop 0
	v_addc_co_u32_e32 v15, vcc, 0, v19, vcc
	v_add_co_u32_e32 v18, vcc, s44, v18
	global_load_dwordx4 v[2:5], v[4:5], off
	s_nop 0
	global_load_dwordx4 v[6:9], v[6:7], off
	v_addc_co_u32_e32 v19, vcc, 0, v19, vcc
	v_lshl_add_u64 v[30:31], v[22:23], 0, s[8:9]
	v_add_co_u32_e32 v22, vcc, s38, v22
	global_load_dwordx4 v[10:13], v[10:11], off
	s_nop 0
	v_addc_co_u32_e32 v23, vcc, 0, v23, vcc
	global_load_dwordx4 v[14:17], v[14:15], off
	s_lshr_b32 s62, s21, 6
	global_load_dwordx4 v[18:21], v[18:19], off
	s_nop 0
	global_load_dwordx4 v[138:141], v[30:31], off offset:32
	global_load_dwordx4 v[134:137], v[30:31], off offset:64
	global_load_dwordx4 v[130:133], v[30:31], off offset:96
	global_load_dwordx4 v[126:129], v[30:31], off offset:128
	global_load_dwordx4 v[122:125], v[30:31], off offset:160
	global_load_dwordx4 v[118:121], v[30:31], off offset:192
	global_load_dwordx4 v[114:117], v[30:31], off offset:224
	global_load_dwordx4 v[110:113], v[30:31], off offset:256
	global_load_dwordx4 v[106:109], v[30:31], off offset:288
	global_load_dwordx4 v[102:105], v[30:31], off offset:320
	global_load_dwordx4 v[142:145], v[22:23], off
	global_load_dwordx4 v[98:101], v[30:31], off offset:352
	v_mad_u64_u32 v[186:187], s[20:21], v24, s39, v[0:1]
	v_mad_u64_u32 v[188:189], s[20:21], v26, s39, v[28:29]
	v_add_u32_e32 v22, 0, v186
	s_and_b32 s20, s31, 12
	s_add_i32 s20, s20, s59
	s_and_b32 s60, s20, 15
	s_or_b32 s63, s61, 3
	s_waitcnt vmcnt(0)
	ds_write_b128 v22, v[2:5]
	ds_write_b128 v22, v[6:9] offset:12800
	v_add_u32_e32 v2, 0, v188
	v_mul_lo_u32 v3, v26, s45
	v_add_u32_e32 v198, v188, v3
	s_lshl_b32 s59, s60, 21
	s_add_u32 s20, s18, s59
	ds_write_b128 v2, v[10:13] offset:256
	v_add_u32_e32 v2, v2, v3
	v_add_u32_e32 v3, 0x6400, v2
	v_add_u32_e32 v2, 0x8600, v2
	ds_write2_b64 v3, v[14:15], v[16:17] offset1:1
	ds_write2_b64 v2, v[18:19], v[20:21] offset1:1
	v_lshlrev_b32_e32 v2, 2, v183
	v_xor_b32_e32 v185, 0x80, v2
	v_lshlrev_b64 v[2:3], 14, v[26:27]
	s_addc_u32 s21, s19, 0
	v_lshl_add_u64 v[190:191], s[20:21], 0, v[2:3]
	s_lshl_b64 s[20:21], s[22:23], 19
	s_add_u32 s20, s20, 0xe002000
	s_addc_u32 s21, s21, 0
	v_lshlrev_b64 v[2:3], 7, v[26:27]
	v_lshl_add_u64 v[192:193], s[20:21], 0, v[2:3]
	s_lshl_b64 s[22:23], s[22:23], 24
	v_lshlrev_b64 v[2:3], 12, v[24:25]
	v_mov_b32_e32 v16, v1
	v_mov_b32_e32 v17, v1
	v_lshlrev_b32_e32 v182, 3, v32
	v_lshlrev_b32_e32 v202, 4, v29
	v_or_b32_e32 v190, v190, v28
	v_or_b32_e32 v192, v192, v28
	v_lshl_add_u64 v[194:195], s[22:23], 0, v[2:3]
	s_lshl_b32 s60, s60, 8
	v_mov_b32_e32 v2, v1
	v_mov_b32_e32 v3, v1
	v_mov_b32_e32 v4, v1
	v_mov_b32_e32 v5, v1
	v_mov_b32_e32 v6, v1
	v_mov_b32_e32 v7, v1
	v_mov_b32_e32 v8, v1
	v_mov_b32_e32 v9, v1
	v_mov_b32_e32 v10, v1
	v_mov_b32_e32 v11, v1
	v_mov_b32_e32 v12, v1
	v_mov_b32_e32 v13, v1
	v_mov_b32_e32 v14, v1
	v_mov_b32_e32 v15, v1
	v_mov_b64_e32 v[32:33], v[16:17]
	v_mov_b64_e32 v[48:49], v[16:17]
	v_mov_b64_e32 v[64:65], v[16:17]
	v_mul_u32_u24_e32 v199, 0x190, v197
	v_mul_u32_u24_e32 v189, 0x88, v197
	v_or3_b32 v194, v194, s60, v0
	v_mov_b32_e32 v170, 0xff800000
	v_mov_b64_e32 v[30:31], v[14:15]
	v_mov_b64_e32 v[28:29], v[12:13]
	v_mov_b64_e32 v[26:27], v[10:11]
	v_mov_b64_e32 v[24:25], v[8:9]
	v_mov_b64_e32 v[22:23], v[6:7]
	v_mov_b64_e32 v[20:21], v[4:5]
	v_mov_b64_e32 v[18:19], v[2:3]
	v_mov_b64_e32 v[46:47], v[14:15]
	v_mov_b64_e32 v[44:45], v[12:13]
	v_mov_b64_e32 v[42:43], v[10:11]
	v_mov_b64_e32 v[40:41], v[8:9]
	v_mov_b64_e32 v[38:39], v[6:7]
	v_mov_b64_e32 v[36:37], v[4:5]
	v_mov_b64_e32 v[34:35], v[2:3]
	v_mov_b64_e32 v[62:63], v[14:15]
	v_mov_b64_e32 v[60:61], v[12:13]
	v_mov_b64_e32 v[58:59], v[10:11]
	v_mov_b64_e32 v[56:57], v[8:9]
	v_mov_b64_e32 v[54:55], v[6:7]
	v_mov_b64_e32 v[52:53], v[4:5]
	v_mov_b64_e32 v[50:51], v[2:3]
	v_mov_b32_e32 v187, 0
	s_mov_b32 s64, s5
	s_waitcnt lgkmcnt(0)
	s_barrier
	s_add_u32 s70, s24, 0x11140000
	s_addc_u32 s71, s25, 0
	s_add_u32 s72, s24, 0x11160000
	s_addc_u32 s73, s25, 0
	s_add_u32 s74, s24, 0x13100000
	s_addc_u32 s75, s25, 0
	s_add_u32 s76, s24, 0x13200000
	s_addc_u32 s77, s25, 0
	s_mov_b64 s[78:79], s[24:25]
; #define LAS __attribute__((address_space(3)))
; DI float shfl_xor_l(float v, int lane, int m) { return __int_as_float(__builtin_amdgcn_ds_bpermute((lane ^ m) << 2, __float_as_int(v))); }
; #define VLD(dst, j, dt) do { LAS unsigned char* va_ = vb + (32 * (dt) + n) * VROW + (16 * (j) + 4 * g) * 2; const u32x2 lo_ = *(const LAS u32x2*)(va_), hi_ = *(const LAS u32x2*)(va_ + 16); dst = (u32x4){lo_.x, lo_.y, hi_.x, hi_.y}; } while (0)
; DI void attn_unit(LAS unsigned char* lds, int wid, int b, int h, int qb) {
;     ...
;     for (int kt = 0; kt < nkt; ++kt) {
;         const int buf = kt & 1;
;         if (kt + 1 < nkt) A_LOAD(kt + 1);
;         if (kt <= cq) {
;             LAS unsigned char* kb = lds + buf * ABUF; LAS unsigned char* vb = kb + KBYTES;
;             f32x16 s0, s1;
; #pragma unroll
;             for (int i = 0; i < 16; ++i) { s0[i] = 0.f; s1[i] = 0.f; }
;     ...
;             bf16x8 ka[3][2];
;             ka[0][0] = KLD(0, 0); ka[0][1] = KLD(0, 1); ka[1][0] = KLD(1, 0); ka[1][1] = KLD(1, 1);
; #pragma unroll
;             for (int ks = 0; ks < 12; ++ks) {
;                 if (ks + 2 < 12) { ka[(ks + 2) % 3][0] = KLD(ks + 2, 0); ka[(ks + 2) % 3][1] = KLD(ks + 2, 1); }
;                 s0 = __builtin_amdgcn_mfma_f32_32x32x16_bf16(ka[ks % 3][0], qf[ks], s0, 0, 0, 0); s1 = __builtin_amdgcn_mfma_f32_32x32x16_bf16(ka[ks % 3][1], qf[ks], s1, 0, 0, 0);
;                 __builtin_amdgcn_sched_barrier(0); }
;             u32x4 vf[2][4];
; #pragma unroll
;             for (int dt = 0; dt < 4; ++dt) VLD(vf[0][dt], 0, dt);
;             float mx = s0[0];
; #pragma unroll
;             for (int i = 1; i < 16; ++i) mx = fmaxf(mx, s0[i]);
; #pragma unroll
;             for (int i = 0; i < 16; ++i) mx = fmaxf(mx, s1[i]);
;             mx = fmaxf(mx, shfl_xor_l(mx, lane, 32));
;             const float mnew = fmaxf(mrow, mx), alpha = __builtin_amdgcn_exp2f(mrow - mnew); mrow = mnew;
;             float ls = 0.f;
; #pragma unroll
;             for (int i = 0; i < 16; ++i) { s0[i] = __builtin_amdgcn_exp2f(s0[i] - mnew); s1[i] = __builtin_amdgcn_exp2f(s1[i] - mnew); ls += s0[i] + s1[i]; }
;             lrow = lrow * alpha + ls;
;             if (__builtin_amdgcn_ballot_w64(alpha != 1.f) != 0ull) {
; #pragma unroll
;                 for (int dt = 0; dt < 4; ++dt)
; #pragma unroll
;                     for (int i = 0; i < 16; ++i) o[dt][i] *= alpha;
.LBB0_1079:
	s_and_b32 s65, s64, 1
	global_load_dwordx4 v[146:149], v194, s[70:71]
	global_load_dwordx4 v[150:153], v194, s[72:73]
	global_load_dwordx4 v[154:157], v192, s[78:79]
	global_load_dwordx4 v[158:161], v190, s[74:75] offset:128
	global_load_dwordx4 v[162:165], v190, s[76:77] offset:128
	s_cmp_gt_u32 s64, s62
	s_cbranch_scc1 .LBB0_1083
	s_mul_i32 s66, s65, 0xa800
	s_add_i32 s66, s66, 0
	v_add3_u32 v171, s66, v199, v202
	ds_read_b128 v[66:69], v171
	ds_read_b128 v[166:169], v171 offset:32
	ds_read_b128 v[82:85], v171 offset:12800
	ds_read_b128 v[172:175], v171 offset:64
	ds_read_b128 v[176:179], v171 offset:12832
	ds_read_b128 v[204:207], v171 offset:12864
	s_waitcnt lgkmcnt(3)
	v_mfma_f32_32x32x16_bf16 v[82:97], v[82:85], v[142:145], 0
	v_mfma_f32_32x32x16_bf16 v[66:81], v[66:69], v[142:145], 0
	v_mfma_f32_32x32x16_bf16 v[66:81], v[166:169], v[138:141], v[66:81]
	ds_read_b128 v[166:169], v171 offset:96
	ds_read_b128 v[208:211], v171 offset:12896
	s_waitcnt lgkmcnt(3)
	v_mfma_f32_32x32x16_bf16 v[82:97], v[176:179], v[138:141], v[82:97]
	v_mfma_f32_32x32x16_bf16 v[66:81], v[172:175], v[134:137], v[66:81]
	ds_read_b128 v[172:175], v171 offset:128
	ds_read_b128 v[176:179], v171 offset:12928
	s_waitcnt lgkmcnt(4)
	v_mfma_f32_32x32x16_bf16 v[82:97], v[204:207], v[134:137], v[82:97]
	s_waitcnt lgkmcnt(3)
	v_mfma_f32_32x32x16_bf16 v[66:81], v[166:169], v[130:133], v[66:81]
	ds_read_b128 v[166:169], v171 offset:160
	ds_read_b128 v[204:207], v171 offset:12960
	s_waitcnt lgkmcnt(4)
	v_mfma_f32_32x32x16_bf16 v[82:97], v[208:211], v[130:133], v[82:97]
	s_waitcnt lgkmcnt(3)
	v_mfma_f32_32x32x16_bf16 v[66:81], v[172:175], v[126:129], v[66:81]
	ds_read_b128 v[172:175], v171 offset:192
	ds_read_b128 v[208:211], v171 offset:12992
	s_waitcnt lgkmcnt(4)
	v_mfma_f32_32x32x16_bf16 v[82:97], v[176:179], v[126:129], v[82:97]
	s_waitcnt lgkmcnt(3)
	v_mfma_f32_32x32x16_bf16 v[66:81], v[166:169], v[122:125], v[66:81]
	ds_read_b128 v[166:169], v171 offset:224
	ds_read_b128 v[176:179], v171 offset:13024
	s_waitcnt lgkmcnt(4)
	v_mfma_f32_32x32x16_bf16 v[82:97], v[204:207], v[122:125], v[82:97]
	s_waitcnt lgkmcnt(3)
	v_mfma_f32_32x32x16_bf16 v[66:81], v[172:175], v[118:121], v[66:81]
	ds_read_b128 v[172:175], v171 offset:256
	ds_read_b128 v[204:207], v171 offset:13056
	s_waitcnt lgkmcnt(4)
	v_mfma_f32_32x32x16_bf16 v[82:97], v[208:211], v[118:121], v[82:97]
	s_waitcnt lgkmcnt(3)
	v_mfma_f32_32x32x16_bf16 v[66:81], v[166:169], v[114:117], v[66:81]
	ds_read_b128 v[166:169], v171 offset:288
	ds_read_b128 v[208:211], v171 offset:13088
	s_waitcnt lgkmcnt(4)
	v_mfma_f32_32x32x16_bf16 v[82:97], v[176:179], v[114:117], v[82:97]
	s_waitcnt lgkmcnt(3)
	v_mfma_f32_32x32x16_bf16 v[66:81], v[172:175], v[110:113], v[66:81]
	ds_read_b128 v[172:175], v171 offset:320
	ds_read_b128 v[176:179], v171 offset:13120
	s_waitcnt lgkmcnt(4)
	v_mfma_f32_32x32x16_bf16 v[82:97], v[204:207], v[110:113], v[82:97]
	s_waitcnt lgkmcnt(3)
	v_mfma_f32_32x32x16_bf16 v[66:81], v[166:169], v[106:109], v[66:81]
	ds_read_b128 v[166:169], v171 offset:352
	ds_read_b128 v[212:215], v171 offset:13152
	s_waitcnt lgkmcnt(4)
	v_mfma_f32_32x32x16_bf16 v[82:97], v[208:211], v[106:109], v[82:97]
	s_waitcnt lgkmcnt(3)
	v_mfma_f32_32x32x16_bf16 v[66:81], v[172:175], v[102:105], v[66:81]
	s_waitcnt lgkmcnt(2)
	v_mfma_f32_32x32x16_bf16 v[82:97], v[176:179], v[102:105], v[82:97]
	s_waitcnt lgkmcnt(1)
	v_mfma_f32_32x32x16_bf16 v[66:81], v[166:169], v[98:101], v[66:81]
	v_add_u32_e32 v171, s66, v184
	v_add_u32_e32 v171, v171, v189
	v_add_u32_e32 v204, 0x6000, v171
	v_add_u32_e32 v205, 0x7000, v171
	v_add_u32_e32 v206, 0x8000, v171
	v_add_u32_e32 v207, 0x9000, v171
	ds_read2_b64 v[166:169], v204 offset0:128 offset1:130
	s_nop 4
	v_max_f32_e32 v172, v67, v67
	v_max_f32_e32 v173, v66, v66
	v_max_f32_e32 v172, v173, v172
	s_waitcnt lgkmcnt(1)
	v_mfma_f32_32x32x16_bf16 v[82:97], v[212:215], v[98:101], v[82:97]
	v_max3_f32 v172, v172, v68, v69
	v_max3_f32 v172, v172, v70, v71
	v_max3_f32 v172, v172, v72, v73
	v_max3_f32 v172, v172, v74, v75
	v_max3_f32 v172, v172, v76, v77
	v_max3_f32 v172, v172, v78, v79
	v_max3_f32 v172, v172, v80, v81
	s_nop 4
	v_max3_f32 v172, v172, v82, v83
	v_max3_f32 v172, v172, v84, v85
	v_max3_f32 v172, v172, v86, v87
	v_max3_f32 v172, v172, v88, v89
	v_max3_f32 v172, v172, v90, v91
	v_max3_f32 v172, v172, v92, v93
	v_max3_f32 v172, v172, v94, v95
	v_max3_f32 v172, v172, v96, v97
	ds_bpermute_b32 v173, v185, v172
	ds_read2_b64 v[178:181], v205 offset0:160 offset1:162
	ds_read2_b64 v[174:177], v206 offset0:192 offset1:194
	s_waitcnt lgkmcnt(2)
	v_max3_f32 v203, v170, v172, v173
	v_mov_b32_e32 v236, v170
	v_sub_f32_e32 v170, v170, v203
	v_cmp_gt_f32_e32 vcc, 0xc1000000, v170
	v_exp_f32_e32 v196, v170
	ds_read2_b64 v[170:173], v207 offset0:224 offset1:226
	s_cbranch_vccz .Lthr_0_keep
	v_pk_mul_f32 v[64:65], v[64:65], v[196:197] op_sel_hi:[1,0]
	v_pk_mul_f32 v[62:63], v[62:63], v[196:197] op_sel_hi:[1,0]
	v_pk_mul_f32 v[60:61], v[60:61], v[196:197] op_sel_hi:[1,0]
	v_pk_mul_f32 v[58:59], v[58:59], v[196:197] op_sel_hi:[1,0]
	v_pk_mul_f32 v[56:57], v[56:57], v[196:197] op_sel_hi:[1,0]
	v_pk_mul_f32 v[54:55], v[54:55], v[196:197] op_sel_hi:[1,0]
	v_pk_mul_f32 v[52:53], v[52:53], v[196:197] op_sel_hi:[1,0]
	v_pk_mul_f32 v[50:51], v[50:51], v[196:197] op_sel_hi:[1,0]
	v_pk_mul_f32 v[48:49], v[48:49], v[196:197] op_sel_hi:[1,0]
	v_pk_mul_f32 v[46:47], v[46:47], v[196:197] op_sel_hi:[1,0]
	v_pk_mul_f32 v[44:45], v[44:45], v[196:197] op_sel_hi:[1,0]
	v_pk_mul_f32 v[42:43], v[42:43], v[196:197] op_sel_hi:[1,0]
	v_pk_mul_f32 v[40:41], v[40:41], v[196:197] op_sel_hi:[1,0]
	v_pk_mul_f32 v[38:39], v[38:39], v[196:197] op_sel_hi:[1,0]
	v_pk_mul_f32 v[36:37], v[36:37], v[196:197] op_sel_hi:[1,0]
	v_pk_mul_f32 v[34:35], v[34:35], v[196:197] op_sel_hi:[1,0]
	v_pk_mul_f32 v[32:33], v[32:33], v[196:197] op_sel_hi:[1,0]
	v_pk_mul_f32 v[30:31], v[30:31], v[196:197] op_sel_hi:[1,0]
	v_pk_mul_f32 v[28:29], v[28:29], v[196:197] op_sel_hi:[1,0]
	v_pk_mul_f32 v[26:27], v[26:27], v[196:197] op_sel_hi:[1,0]
	v_pk_mul_f32 v[24:25], v[24:25], v[196:197] op_sel_hi:[1,0]
	v_pk_mul_f32 v[22:23], v[22:23], v[196:197] op_sel_hi:[1,0]
	v_pk_mul_f32 v[20:21], v[20:21], v[196:197] op_sel_hi:[1,0]
	v_pk_mul_f32 v[18:19], v[18:19], v[196:197] op_sel_hi:[1,0]
	v_pk_mul_f32 v[16:17], v[16:17], v[196:197] op_sel_hi:[1,0]
	v_pk_mul_f32 v[14:15], v[14:15], v[196:197] op_sel_hi:[1,0]
	v_pk_mul_f32 v[12:13], v[12:13], v[196:197] op_sel_hi:[1,0]
	v_pk_mul_f32 v[10:11], v[10:11], v[196:197] op_sel_hi:[1,0]
	v_pk_mul_f32 v[8:9], v[8:9], v[196:197] op_sel_hi:[1,0]
	v_pk_mul_f32 v[6:7], v[6:7], v[196:197] op_sel_hi:[1,0]
	v_pk_mul_f32 v[4:5], v[4:5], v[196:197] op_sel_hi:[1,0]
	v_pk_mul_f32 v[2:3], v[2:3], v[196:197] op_sel_hi:[1,0]

; #define A_LOAD(kt) do { const size_t ko = (size_t)(kt) * 64; st0 = *(const u32x4*)(kn_src + ko * 2048); st1 = *(const u32x4*)(kn_src + (ko + 32) * 2048); \
;         st2 = *(const u32x4*)(kr_src + ko * 64); st3 = *(const u32x4*)(v_src + ko); st4 = *(const u32x4*)(v_src + ko + (size_t)64 * 8192); } while (0)
; DI void attn_unit(LAS unsigned char* lds, int wid, int b, int h, int qb) {
;     ...
;         if (kt + 1 < nkt) A_LOAD(kt + 1);
;     ...
;         if (kt + 1 < nkt) A_WRITE(buf ^ 1);
.LBB0_1084:
	s_add_u32 s70, s70, 0x40000
	s_addc_u32 s71, s71, 0
	s_add_u32 s72, s72, 0x40000
	s_addc_u32 s73, s73, 0
	s_add_u32 s78, s78, 0x2000
	s_addc_u32 s79, s79, 0
	s_add_u32 s74, s74, 0x80
	s_addc_u32 s75, s75, 0
	s_add_u32 s76, s76, 0x80
	s_addc_u32 s77, s77, 0
	s_xor_b32 s65, s65, 1
	s_mul_i32 s65, s65, 0xa800
	s_add_i32 s65, s65, 0
	v_add_u32_e32 v66, s65, v186
	s_waitcnt vmcnt(4)
	ds_write_b128 v66, v[146:149]
	s_waitcnt vmcnt(3)
	ds_write_b128 v66, v[150:153] offset:12800
	v_add_u32_e32 v66, s65, v188
	s_add_i32 s64, s64, 1
	s_waitcnt vmcnt(2)
	ds_write_b128 v66, v[154:157] offset:256
	v_add_u32_e32 v66, s65, v198
	v_add_u32_e32 v67, 0x6400, v66
	v_add_u32_e32 v66, 0x8600, v66


; DI void attn_unit(LAS unsigned char* lds, int wid, int b, int h, int qb) {
;     ...
;     for (int kt = 0; kt < nkt; ++kt) {
	s_cmp_eq_u32 s63, s64

; DI void attn_unit(LAS unsigned char* lds, int wid, int b, int h, int qb) {
;     ...
;         if (kt + 1 < nkt) A_WRITE(buf ^ 1);
;         __syncthreads();
	s_waitcnt vmcnt(1)
	ds_write2_b64 v67, v[158:159], v[160:161] offset1:1
	s_waitcnt vmcnt(0)
	ds_write2_b64 v66, v[162:163], v[164:165] offset1:1
	s_waitcnt lgkmcnt(0)
	s_barrier
	s_cbranch_scc1 .LBB0_1086
	v_mov_b32_e32 v170, v203
	s_branch .LBB0_1079

; #define LAS __attribute__((address_space(3)))
; DI u32x2 pk4(f32x4 v) { u32x2 r; r.x = pk2(v[0], v[1]); r.y = pk2(v[2], v[3]); return r; }
; DI float shfl_xor_l(float v, int lane, int m) { return __int_as_float(__builtin_amdgcn_ds_bpermute((lane ^ m) << 2, __float_as_int(v))); }
; DI void attn_unit(LAS unsigned char* lds, int wid, int b, int h, int qb) {
;     ...
;     const float lt = lrow + shfl_xor_l(lrow, lane, 32), inv = 1.f / lt;
;     LAS unsigned char* pt_ = lds + ABUF + wid * (32 * 272);
; #pragma unroll
;     for (int dt = 0; dt < 4; ++dt)
; #pragma unroll
;         for (int blk = 0; blk < 4; ++blk) { const f32x4 v = {o[dt][4 * blk] * inv, o[dt][4 * blk + 1] * inv, o[dt][4 * blk + 2] * inv, o[dt][4 * blk + 3] * inv};
;             *(LAS u32x2*)(pt_ + n * 272 + (32 * dt + 8 * blk + 4 * g) * 2) = pk4(v); }
;     asm volatile("" ::: "memory");
;     bf16_t* od = WSB(OFF_O) + ((size_t)b * SEQ + q0 + (lane >> 4)) * 2048 + h * 128 + (lane & 15) * 8;
; #pragma unroll
;     for (int j = 0; j < 8; ++j) { const u32x4 w = *(const LAS u32x4*)(pt_ + (4 * j + (lane >> 4)) * 272 + (lane & 15) * 16); *(u32x4*)(od + (size_t)(4 * j) * 2048) = w; }
.LBB0_1090:
	ds_bpermute_b32 v66, v185, v187
	s_waitcnt lgkmcnt(0)
	s_barrier
	v_mov_b32_e32 v185, v1
	v_add_f32_e32 v66, v187, v66
	v_div_scale_f32 v67, s[62:63], v66, v66, 1.0
	v_rcp_f32_e32 v68, v67
	v_div_scale_f32 v69, vcc, 1.0, v66, 1.0
	v_mov_b32_e32 v187, v201
	v_fma_f32 v70, -v67, v68, 1.0
	v_fmac_f32_e32 v68, v70, v68
	v_mul_f32_e32 v70, v69, v68
	v_fma_f32 v71, -v67, v70, v69
	v_fmac_f32_e32 v70, v71, v68
	v_fma_f32 v67, -v67, v70, v69
	v_div_fmas_f32 v67, v67, v68, v70
	v_div_fixup_f32 v66, v67, v66, 1.0
	v_mul_u32_u24_e32 v67, 0x110, v197
	v_add3_u32 v67, s30, v67, v184
	v_pk_mul_f32 v[2:3], v[2:3], v[66:67] op_sel_hi:[1,0]
	v_pk_mul_f32 v[4:5], v[4:5], v[66:67] op_sel_hi:[1,0]
	v_pk_mul_f32 v[50:51], v[50:51], v[66:67] op_sel_hi:[1,0]
	v_pk_mul_f32 v[52:53], v[52:53], v[66:67] op_sel_hi:[1,0]
	v_cvt_pk_bf16_f32 v2, v2, v3
	v_cvt_pk_bf16_f32 v3, v4, v5
	v_pk_mul_f32 v[4:5], v[6:7], v[66:67] op_sel_hi:[1,0]
	v_pk_mul_f32 v[6:7], v[8:9], v[66:67] op_sel_hi:[1,0]
	v_cvt_pk_bf16_f32 v50, v50, v51
	v_cvt_pk_bf16_f32 v51, v52, v53
	v_pk_mul_f32 v[52:53], v[54:55], v[66:67] op_sel_hi:[1,0]
	v_pk_mul_f32 v[54:55], v[56:57], v[66:67] op_sel_hi:[1,0]
	v_add_u32_e32 v56, 0xa800, v67
	v_cvt_pk_bf16_f32 v4, v4, v5
	v_cvt_pk_bf16_f32 v5, v6, v7
	ds_write2_b64 v56, v[2:3], v[4:5] offset0:24 offset1:26
	v_pk_mul_f32 v[2:3], v[10:11], v[66:67] op_sel_hi:[1,0]
	v_pk_mul_f32 v[4:5], v[12:13], v[66:67] op_sel_hi:[1,0]
	v_pk_mul_f32 v[34:35], v[34:35], v[66:67] op_sel_hi:[1,0]
	v_pk_mul_f32 v[36:37], v[36:37], v[66:67] op_sel_hi:[1,0]
	v_pk_mul_f32 v[18:19], v[18:19], v[66:67] op_sel_hi:[1,0]
	v_pk_mul_f32 v[20:21], v[20:21], v[66:67] op_sel_hi:[1,0]
	v_cvt_pk_bf16_f32 v2, v2, v3
	v_cvt_pk_bf16_f32 v3, v4, v5
	v_pk_mul_f32 v[4:5], v[14:15], v[66:67] op_sel_hi:[1,0]
	v_pk_mul_f32 v[6:7], v[16:17], v[66:67] op_sel_hi:[1,0]
	v_cvt_pk_bf16_f32 v34, v34, v35
	v_cvt_pk_bf16_f32 v35, v36, v37
	v_pk_mul_f32 v[36:37], v[38:39], v[66:67] op_sel_hi:[1,0]
	v_pk_mul_f32 v[38:39], v[40:41], v[66:67] op_sel_hi:[1,0]
	v_cvt_pk_bf16_f32 v18, v18, v19
	v_cvt_pk_bf16_f32 v19, v20, v21
	v_pk_mul_f32 v[20:21], v[22:23], v[66:67] op_sel_hi:[1,0]
	v_pk_mul_f32 v[22:23], v[24:25], v[66:67] op_sel_hi:[1,0]
	v_cvt_pk_bf16_f32 v4, v4, v5
	v_cvt_pk_bf16_f32 v5, v6, v7
	v_cvt_pk_bf16_f32 v52, v52, v53
	v_cvt_pk_bf16_f32 v53, v54, v55
	v_cvt_pk_bf16_f32 v36, v36, v37
	v_cvt_pk_bf16_f32 v37, v38, v39
	v_cvt_pk_bf16_f32 v20, v20, v21
	v_cvt_pk_bf16_f32 v21, v22, v23
	ds_write2_b64 v56, v[2:3], v[4:5] offset0:28 offset1:30
	v_ashrrev_i32_e32 v2, 4, v183
	ds_write2_b64 v56, v[50:51], v[52:53] offset1:2
	v_pk_mul_f32 v[50:51], v[58:59], v[66:67] op_sel_hi:[1,0]
	v_pk_mul_f32 v[52:53], v[60:61], v[66:67] op_sel_hi:[1,0]
	ds_write2_b64 v56, v[34:35], v[36:37] offset0:8 offset1:10
	v_pk_mul_f32 v[34:35], v[42:43], v[66:67] op_sel_hi:[1,0]
	v_pk_mul_f32 v[36:37], v[44:45], v[66:67] op_sel_hi:[1,0]
	ds_write2_b64 v56, v[18:19], v[20:21] offset0:16 offset1:18
	v_pk_mul_f32 v[18:19], v[26:27], v[66:67] op_sel_hi:[1,0]
	v_pk_mul_f32 v[20:21], v[28:29], v[66:67] op_sel_hi:[1,0]
	v_ashrrev_i32_e32 v3, 31, v2
	v_cvt_pk_bf16_f32 v50, v50, v51
	v_cvt_pk_bf16_f32 v51, v52, v53
	v_pk_mul_f32 v[52:53], v[62:63], v[66:67] op_sel_hi:[1,0]
	v_pk_mul_f32 v[54:55], v[64:65], v[66:67] op_sel_hi:[1,0]
	v_cvt_pk_bf16_f32 v34, v34, v35
	v_cvt_pk_bf16_f32 v35, v36, v37
	v_pk_mul_f32 v[36:37], v[46:47], v[66:67] op_sel_hi:[1,0]
	v_pk_mul_f32 v[38:39], v[48:49], v[66:67] op_sel_hi:[1,0]
	v_cvt_pk_bf16_f32 v18, v18, v19
	v_cvt_pk_bf16_f32 v19, v20, v21
	v_pk_mul_f32 v[20:21], v[30:31], v[66:67] op_sel_hi:[1,0]
	v_pk_mul_f32 v[22:23], v[32:33], v[66:67] op_sel_hi:[1,0]
	v_lshl_add_u64 v[4:5], s[26:27], 0, v[2:3]
	v_cvt_pk_bf16_f32 v52, v52, v53
	v_cvt_pk_bf16_f32 v53, v54, v55
	v_cvt_pk_bf16_f32 v36, v36, v37
	v_cvt_pk_bf16_f32 v37, v38, v39
	v_cvt_pk_bf16_f32 v20, v20, v21
	v_cvt_pk_bf16_f32 v21, v22, v23
	v_lshlrev_b64 v[4:5], 12, v[4:5]
	ds_write2_b64 v56, v[50:51], v[52:53] offset0:4 offset1:6
	ds_write2_b64 v56, v[34:35], v[36:37] offset0:12 offset1:14
	ds_write2_b64 v56, v[18:19], v[20:21] offset0:20 offset1:22
	v_lshl_add_u64 v[4:5], s[24:25], 0, v[4:5]
	s_lshl_b32 s24, s4, 1
	s_mov_b32 s25, s5
	v_mul_lo_u32 v2, v2, s46
	v_lshl_add_u64 v[4:5], v[4:5], 0, s[24:25]
	v_lshlrev_b32_e32 v6, 1, v182
	v_mov_b32_e32 v7, v1
	v_add3_u32 v0, s30, v0, v2
	v_lshl_add_u64 v[10:11], v[4:5], 0, v[6:7]
	ds_read_b128 v[2:5], v0 offset:43008
	ds_read_b128 v[6:9], v0 offset:44096
	v_add_co_u32_e32 v12, vcc, s47, v10
	s_mov_b64 s[26:27], s[0:1]
	s_nop 0
	v_addc_co_u32_e32 v13, vcc, 0, v11, vcc
	s_waitcnt lgkmcnt(1)
	global_store_dwordx4 v[12:13], v[2:5], off
	v_mov_b32_e32 v172, 0xff800000
	s_nop 0
	v_add_co_u32_e32 v2, vcc, s48, v10
	s_nop 1
	v_addc_co_u32_e32 v3, vcc, 0, v11, vcc
	s_waitcnt lgkmcnt(0)
	global_store_dwordx4 v[2:3], v[6:9], off
	ds_read_b128 v[2:5], v0 offset:45184
	ds_read_b128 v[6:9], v0 offset:46272
	v_add_co_u32_e32 v12, vcc, s49, v10
	s_nop 1
	v_addc_co_u32_e32 v13, vcc, 0, v11, vcc
	s_waitcnt lgkmcnt(1)
	global_store_dwordx4 v[12:13], v[2:5], off
	s_nop 1
	v_add_co_u32_e32 v2, vcc, s50, v10
	s_nop 1
	v_addc_co_u32_e32 v3, vcc, 0, v11, vcc
	s_waitcnt lgkmcnt(0)
	global_store_dwordx4 v[2:3], v[6:9], off
	ds_read_b128 v[2:5], v0 offset:47360
	ds_read_b128 v[6:9], v0 offset:48448
	v_add_co_u32_e32 v12, vcc, s51, v10
	s_nop 1
	v_addc_co_u32_e32 v13, vcc, 0, v11, vcc
	s_waitcnt lgkmcnt(1)
	global_store_dwordx4 v[12:13], v[2:5], off
	s_nop 1
	v_add_co_u32_e32 v2, vcc, s52, v10
	s_nop 1
	v_addc_co_u32_e32 v3, vcc, 0, v11, vcc
	s_waitcnt lgkmcnt(0)
; #define LAS __attribute__((address_space(3)))
; DI CP* kparams() { CP* kp = (CP*)__builtin_amdgcn_kernarg_segment_ptr(); asm volatile("" : "+s"(kp)); return kp; }
; DI int lane_id() { int l = __builtin_amdgcn_mbcnt_hi(-1, __builtin_amdgcn_mbcnt_lo(-1, 0)); asm volatile("" : "+v"(l)); return l; }
; #define A_LOAD(kt) do { const size_t ko = (size_t)(kt) * 64; st0 = *(const u32x4*)(kn_src + ko * 2048); st1 = *(const u32x4*)(kn_src + (ko + 32) * 2048); \
;         st2 = *(const u32x4*)(kr_src + ko * 64); st3 = *(const u32x4*)(v_src + ko); st4 = *(const u32x4*)(v_src + ko + (size_t)64 * 8192); } while (0)
; DI void attn_unit(LAS unsigned char* lds, int wid, int b, int h, int qb) {
;     CP& p = *kparams();
;     const int lane = lane_id(), tid = wid * 64 + lane, n = lane & 31, g = lane >> 5;
;     const int q0 = qb * 256 + wid * 32, cq = q0 >> 6, nkt = 4 * qb + 4;
;     const size_t tokq = (size_t)b * SEQ + q0 + n;
;     const bf16_t* Q = WSB(OFF_Q); const bf16_t* KN = WSB(OFF_KN); const bf16_t* KR = WSB(OFF_KR); const bf16_t* VT = WSB(OFF_VT2);
;     bf16x8 qf[12];
; #pragma unroll
;     for (int ks = 0; ks < 12; ++ks) qf[ks] = *(const bf16x8*)(Q + tokq * 3072 + h * 192 + ks * 16 + g * 8);
;     f32x16 o[4];
; #pragma unroll
;     for (int dt = 0; dt < 4; ++dt)
; #pragma unroll
;         for (int i = 0; i < 16; ++i) o[dt][i] = 0.f;
;     float mrow = -__builtin_inff(), lrow = 0.f;
;     const int krow = tid >> 4, kc16 = tid & 15, rrow = tid >> 3, rc8 = tid & 7;
;     const bf16_t* kn_src = KN + ((size_t)b * SEQ + krow) * 2048 + h * 128 + kc16 * 8;
;     const bf16_t* kr_src = KR + ((size_t)b * SEQ + rrow) * 64 + rc8 * 8;
;     const bf16_t* v_src = VT + ((size_t)h * 128 + rrow) * 8192 + (size_t)b * SEQ + rc8 * 8;
;     const int kn_dst = krow * KROW + kc16 * 16, kr_dst = rrow * KROW + 256 + rc8 * 16, v_dst = KBYTES + rrow * VROW + rc8 * 16;
;     u32x4 st0, st1, st2, st3, st4;
;     ...
;     A_LOAD(0); A_WRITE(0); __syncthreads();
;     ...
;     bf16_t* od = WSB(OFF_O) + ((size_t)b * SEQ + q0 + (lane >> 4)) * 2048 + h * 128 + (lane & 15) * 8;
; #pragma unroll
;     for (int j = 0; j < 8; ++j) { const u32x4 w = *(const LAS u32x4*)(pt_ + (4 * j + (lane >> 4)) * 272 + (lane & 15) * 16); *(u32x4*)(od + (size_t)(4 * j) * 2048) = w; }
	global_store_dwordx4 v[2:3], v[6:9], off
	ds_read_b128 v[2:5], v0 offset:49536
	ds_read_b128 v[6:9], v0 offset:50624
	v_add_co_u32_e32 v12, vcc, s53, v10
	s_nop 1
	v_addc_co_u32_e32 v13, vcc, 0, v11, vcc
	s_waitcnt lgkmcnt(1)
	global_store_dwordx4 v[12:13], v[2:5], off
	s_nop 1
	v_add_co_u32_e32 v2, vcc, s54, v10
	s_nop 1
	v_addc_co_u32_e32 v3, vcc, 0, v11, vcc
	s_waitcnt lgkmcnt(0)
	global_store_dwordx4 v[2:3], v[6:9], off
	s_load_dwordx2 s[26:27], s[26:27], 0xa8
	v_add_u32_e32 v0, s28, v187
	v_ashrrev_i32_e32 v24, 3, v0
	v_ashrrev_i32_e32 v25, 31, v24
	v_ashrrev_i32_e32 v22, 4, v0
	v_lshl_add_u64 v[4:5], s[16:17], 0, v[24:25]
	v_ashrrev_i32_e32 v23, 31, v22
	v_lshlrev_b64 v[4:5], 7, v[4:5]
	v_lshlrev_b32_e32 v0, 4, v187
	v_lshl_add_u64 v[2:3], s[16:17], 0, v[22:23]
	s_waitcnt lgkmcnt(0)
	v_lshl_add_u64 v[4:5], s[26:27], 0, v[4:5]
	v_and_b32_e32 v0, 0x70, v0
	v_lshlrev_b64 v[2:3], 12, v[2:3]
	v_lshl_add_u64 v[10:11], v[4:5], 0, v[0:1]
	v_lshl_add_u64 v[4:5], v[24:25], 0, s[4:5]
	v_and_b32_e32 v30, 15, v187
	v_lshl_add_u64 v[2:3], s[26:27], 0, v[2:3]
	v_lshlrev_b64 v[4:5], 14, v[4:5]
	v_lshl_add_u64 v[2:3], v[2:3], 0, s[24:25]
	v_lshlrev_b32_e32 v184, 4, v30
	v_lshl_add_u64 v[4:5], s[26:27], 0, v[4:5]
	v_lshl_add_u64 v[2:3], v[2:3], 0, v[184:185]
	v_lshl_add_u64 v[4:5], s[16:17], 1, v[4:5]
	v_lshl_add_u64 v[18:19], v[4:5], 0, v[0:1]
	v_add_co_u32_e32 v4, vcc, s40, v2
	s_and_b32 s4, s57, 7
	s_nop 0
	v_addc_co_u32_e32 v5, vcc, 0, v3, vcc
	v_add_co_u32_e32 v6, vcc, s41, v2
	s_lshl_b32 s4, s4, 2
	s_lshl_b32 s25, s56, 8
	v_addc_co_u32_e32 v7, vcc, 0, v3, vcc
	s_or_b32 s4, s4, 3
	s_add_i32 s25, s25, s29
	v_add_co_u32_e32 v10, vcc, s42, v10
	v_and_b32_e32 v202, 31, v187
	s_add_u32 s16, s16, s25
	v_addc_co_u32_e32 v11, vcc, 0, v11, vcc
	v_or_b32_e32 v28, s16, v202
	v_mov_b64_e32 v[26:27], s[26:27]
	v_add_co_u32_e32 v14, vcc, s43, v18
	v_ashrrev_i32_e32 v31, 5, v187
	s_addc_u32 s17, s17, 0
	v_mad_u64_u32 v[26:27], s[62:63], v28, s37, v[26:27]
	v_addc_co_u32_e32 v15, vcc, 0, v19, vcc
	v_mad_i32_i24 v27, s17, v200, v27
	s_lshl_b32 s62, s58, 1
	s_mov_b32 s63, s5
	v_lshlrev_b32_e32 v188, 3, v31
	v_add_co_u32_e32 v18, vcc, s44, v18
	v_lshl_add_u64 v[26:27], v[26:27], 0, s[62:63]
	v_ashrrev_i32_e32 v189, 31, v188
	global_load_dwordx4 v[2:5], v[4:5], off
	s_nop 0
	global_load_dwordx4 v[6:9], v[6:7], off
	v_addc_co_u32_e32 v19, vcc, 0, v19, vcc
	v_lshl_add_u64 v[26:27], v[188:189], 1, v[26:27]
	global_load_dwordx4 v[10:13], v[10:11], off
	v_lshl_add_u64 v[28:29], v[26:27], 0, s[8:9]
	v_add_co_u32_e32 v26, vcc, s38, v26
	global_load_dwordx4 v[14:17], v[14:15], off
	s_nop 0
	v_addc_co_u32_e32 v27, vcc, 0, v27, vcc
	global_load_dwordx4 v[18:21], v[18:19], off
	s_nop 0
	global_load_dwordx4 v[152:155], v[28:29], off offset:32
	global_load_dwordx4 v[148:151], v[28:29], off offset:64
	global_load_dwordx4 v[144:147], v[28:29], off offset:96
	global_load_dwordx4 v[140:143], v[28:29], off offset:128
	global_load_dwordx4 v[136:139], v[28:29], off offset:160
	global_load_dwordx4 v[132:135], v[28:29], off offset:192
	global_load_dwordx4 v[128:131], v[28:29], off offset:224
	global_load_dwordx4 v[124:127], v[28:29], off offset:256
	global_load_dwordx4 v[120:123], v[28:29], off offset:288
	global_load_dwordx4 v[116:119], v[28:29], off offset:320
	global_load_dwordx4 v[156:159], v[26:27], off
	global_load_dwordx4 v[112:115], v[28:29], off offset:352
	v_mad_u64_u32 v[190:191], s[62:63], v22, s39, v[184:185]
	v_add_u32_e32 v26, 0, v190
	v_mad_u64_u32 v[192:193], s[62:63], v24, s39, v[0:1]
	s_waitcnt vmcnt(16)
	ds_write_b128 v26, v[2:5]
	s_waitcnt vmcnt(15)
	ds_write_b128 v26, v[6:9] offset:12800
	v_add_u32_e32 v2, 0, v192
	v_mul_lo_u32 v3, v24, s45
	s_lshr_b32 s25, s25, 6
	s_waitcnt vmcnt(14)
	ds_write_b128 v2, v[10:13] offset:256
	v_add_u32_e32 v2, v2, v3
	v_add_u32_e32 v203, v192, v3
	v_add_u32_e32 v3, 0x6400, v2
	v_add_u32_e32 v2, 0x8600, v2
	s_add_u32 s18, s18, s59
	s_waitcnt vmcnt(13)
	ds_write2_b64 v3, v[14:15], v[16:17] offset1:1
	s_waitcnt vmcnt(12)
	ds_write2_b64 v2, v[18:19], v[20:21] offset1:1
	v_lshlrev_b32_e32 v2, 2, v187
	v_xor_b32_e32 v189, 0x80, v2
	v_lshlrev_b64 v[2:3], 14, v[24:25]
	s_addc_u32 s19, s19, 0
	v_lshl_add_u64 v[2:3], s[18:19], 0, v[2:3]
	v_lshl_add_u64 v[194:195], v[2:3], 0, v[0:1]
	v_lshlrev_b64 v[2:3], 7, v[24:25]
	v_lshl_add_u64 v[2:3], s[20:21], 0, v[2:3]
	s_add_u32 s18, s60, s22
	v_lshl_add_u64 v[196:197], v[2:3], 0, v[0:1]
	v_lshlrev_b64 v[2:3], 12, v[22:23]
	s_addc_u32 s19, 0, s23
	v_lshl_add_u64 v[2:3], s[18:19], 0, v[2:3]
	v_mov_b32_e32 v14, v1
	v_mov_b32_e32 v15, v1
	v_lshlrev_b32_e32 v186, 3, v30
	v_lshlrev_b32_e32 v204, 4, v31
	v_lshl_add_u64 v[198:199], v[2:3], 0, v[184:185]
	v_mov_b32_e32 v0, v1
	v_mov_b32_e32 v2, v1
	v_mov_b32_e32 v3, v1
	v_mov_b32_e32 v4, v1
	v_mov_b32_e32 v5, v1
	v_mov_b32_e32 v6, v1
	v_mov_b32_e32 v7, v1
	v_mov_b32_e32 v8, v1
	v_mov_b32_e32 v9, v1
	v_mov_b32_e32 v10, v1
	v_mov_b32_e32 v11, v1
	v_mov_b32_e32 v12, v1
	v_mov_b32_e32 v13, v1
	v_mov_b64_e32 v[30:31], v[14:15]
	v_mov_b64_e32 v[46:47], v[14:15]
	v_mov_b64_e32 v[62:63], v[14:15]
	v_mov_b64_e32 v[78:79], v[14:15]
	s_mov_b32 s57, 0
	v_mul_u32_u24_e32 v193, 0x190, v202
	v_mul_u32_u24_e32 v191, 0x88, v202
	v_mov_b32_e32 v185, 0
	v_mov_b64_e32 v[28:29], v[12:13]
	v_mov_b64_e32 v[26:27], v[10:11]
	v_mov_b64_e32 v[24:25], v[8:9]
	v_mov_b64_e32 v[22:23], v[6:7]
	v_mov_b64_e32 v[20:21], v[4:5]
	v_mov_b64_e32 v[18:19], v[2:3]
	v_mov_b64_e32 v[16:17], v[0:1]
	v_mov_b64_e32 v[44:45], v[12:13]
	v_mov_b64_e32 v[42:43], v[10:11]
	v_mov_b64_e32 v[40:41], v[8:9]
	v_mov_b64_e32 v[38:39], v[6:7]
	v_mov_b64_e32 v[36:37], v[4:5]
	v_mov_b64_e32 v[34:35], v[2:3]
	v_mov_b64_e32 v[32:33], v[0:1]
	v_mov_b64_e32 v[60:61], v[12:13]
	v_mov_b64_e32 v[58:59], v[10:11]
	v_mov_b64_e32 v[56:57], v[8:9]
	v_mov_b64_e32 v[54:55], v[6:7]
	v_mov_b64_e32 v[52:53], v[4:5]
	v_mov_b64_e32 v[50:51], v[2:3]
	v_mov_b64_e32 v[48:49], v[0:1]
	v_mov_b64_e32 v[76:77], v[12:13]
	v_mov_b64_e32 v[74:75], v[10:11]
	v_mov_b64_e32 v[72:73], v[8:9]
	v_mov_b64_e32 v[70:71], v[6:7]
	v_mov_b64_e32 v[68:69], v[4:5]
	v_mov_b64_e32 v[66:67], v[2:3]
	v_mov_b64_e32 v[64:65], v[0:1]
	s_waitcnt lgkmcnt(0)
	s_barrier
	s_add_u32 s70, s26, 0x11140000
	s_addc_u32 s71, s27, 0
	s_add_u32 s72, s26, 0x11160000
	s_addc_u32 s73, s27, 0
	s_add_u32 s74, s26, 0x13100000
	s_addc_u32 s75, s27, 0
	s_add_u32 s76, s26, 0x13200000
	s_addc_u32 s77, s27, 0
	s_mov_b64 s[78:79], s[26:27]
; #define LAS __attribute__((address_space(3)))
; DI float shfl_xor_l(float v, int lane, int m) { return __int_as_float(__builtin_amdgcn_ds_bpermute((lane ^ m) << 2, __float_as_int(v))); }
; #define VLD(dst, j, dt) do { LAS unsigned char* va_ = vb + (32 * (dt) + n) * VROW + (16 * (j) + 4 * g) * 2; const u32x2 lo_ = *(const LAS u32x2*)(va_), hi_ = *(const LAS u32x2*)(va_ + 16); dst = (u32x4){lo_.x, lo_.y, hi_.x, hi_.y}; } while (0)
; DI void attn_unit(LAS unsigned char* lds, int wid, int b, int h, int qb) {
;     ...
;     for (int kt = 0; kt < nkt; ++kt) {
;         const int buf = kt & 1;
;         if (kt + 1 < nkt) A_LOAD(kt + 1);
;         if (kt <= cq) {
;             LAS unsigned char* kb = lds + buf * ABUF; LAS unsigned char* vb = kb + KBYTES;
;             f32x16 s0, s1;
; #pragma unroll
;             for (int i = 0; i < 16; ++i) { s0[i] = 0.f; s1[i] = 0.f; }
;     ...
;             bf16x8 ka[3][2];
;             ka[0][0] = KLD(0, 0); ka[0][1] = KLD(0, 1); ka[1][0] = KLD(1, 0); ka[1][1] = KLD(1, 1);
; #pragma unroll
;             for (int ks = 0; ks < 12; ++ks) {
;                 if (ks + 2 < 12) { ka[(ks + 2) % 3][0] = KLD(ks + 2, 0); ka[(ks + 2) % 3][1] = KLD(ks + 2, 1); }
;                 s0 = __builtin_amdgcn_mfma_f32_32x32x16_bf16(ka[ks % 3][0], qf[ks], s0, 0, 0, 0); s1 = __builtin_amdgcn_mfma_f32_32x32x16_bf16(ka[ks % 3][1], qf[ks], s1, 0, 0, 0);
;                 __builtin_amdgcn_sched_barrier(0); }
;             u32x4 vf[2][4];
; #pragma unroll
;             for (int dt = 0; dt < 4; ++dt) VLD(vf[0][dt], 0, dt);
;             float mx = s0[0];
; #pragma unroll
;             for (int i = 1; i < 16; ++i) mx = fmaxf(mx, s0[i]);
; #pragma unroll
;             for (int i = 0; i < 16; ++i) mx = fmaxf(mx, s1[i]);
;             mx = fmaxf(mx, shfl_xor_l(mx, lane, 32));
;             const float mnew = fmaxf(mrow, mx), alpha = __builtin_amdgcn_exp2f(mrow - mnew); mrow = mnew;
;             float ls = 0.f;
; #pragma unroll
;             for (int i = 0; i < 16; ++i) { s0[i] = __builtin_amdgcn_exp2f(s0[i] - mnew); s1[i] = __builtin_amdgcn_exp2f(s1[i] - mnew); ls += s0[i] + s1[i]; }
;             lrow = lrow * alpha + ls;
;             if (__builtin_amdgcn_ballot_w64(alpha != 1.f) != 0ull) {
; #pragma unroll
;                 for (int dt = 0; dt < 4; ++dt)
; #pragma unroll
;                     for (int i = 0; i < 16; ++i) o[dt][i] *= alpha;
.LBB0_1091:
	s_and_b32 s18, s57, 1
	global_load_dwordx4 v[2:5], v198, s[70:71]
	global_load_dwordx4 v[6:9], v198, s[72:73]
	global_load_dwordx4 v[10:13], v196, s[78:79]
	global_load_dwordx4 v[160:163], v194, s[74:75] offset:128
	global_load_dwordx4 v[164:167], v194, s[76:77] offset:128
	s_cmp_gt_u32 s57, s25
	s_cbranch_scc1 .LBB0_1095
	s_mul_i32 s19, s18, 0xa800
	s_add_i32 s19, s19, 0
	v_add3_u32 v0, s19, v193, v204
	ds_read_b128 v[80:83], v0
	ds_read_b128 v[168:171], v0 offset:32
	ds_read_b128 v[96:99], v0 offset:12800
	ds_read_b128 v[174:177], v0 offset:64
	ds_read_b128 v[178:181], v0 offset:12832
	ds_read_b128 v[206:209], v0 offset:12864
	s_waitcnt vmcnt(6) lgkmcnt(3)
	v_mfma_f32_32x32x16_bf16 v[96:111], v[96:99], v[156:159], 0
	v_mfma_f32_32x32x16_bf16 v[80:95], v[80:83], v[156:159], 0
	v_mfma_f32_32x32x16_bf16 v[80:95], v[168:171], v[152:155], v[80:95]
	ds_read_b128 v[168:171], v0 offset:96
	ds_read_b128 v[210:213], v0 offset:12896
	s_waitcnt lgkmcnt(3)
	v_mfma_f32_32x32x16_bf16 v[96:111], v[178:181], v[152:155], v[96:111]
	v_mfma_f32_32x32x16_bf16 v[80:95], v[174:177], v[148:151], v[80:95]
	ds_read_b128 v[174:177], v0 offset:128
	ds_read_b128 v[178:181], v0 offset:12928
	s_waitcnt lgkmcnt(4)
	v_mfma_f32_32x32x16_bf16 v[96:111], v[206:209], v[148:151], v[96:111]
	s_waitcnt lgkmcnt(3)
	v_mfma_f32_32x32x16_bf16 v[80:95], v[168:171], v[144:147], v[80:95]
	ds_read_b128 v[168:171], v0 offset:160
	ds_read_b128 v[206:209], v0 offset:12960
	s_waitcnt lgkmcnt(4)
	v_mfma_f32_32x32x16_bf16 v[96:111], v[210:213], v[144:147], v[96:111]
	s_waitcnt lgkmcnt(3)
	v_mfma_f32_32x32x16_bf16 v[80:95], v[174:177], v[140:143], v[80:95]
	ds_read_b128 v[174:177], v0 offset:192
	ds_read_b128 v[210:213], v0 offset:12992
	s_waitcnt lgkmcnt(4)
	v_mfma_f32_32x32x16_bf16 v[96:111], v[178:181], v[140:143], v[96:111]
	s_waitcnt lgkmcnt(3)
	v_mfma_f32_32x32x16_bf16 v[80:95], v[168:171], v[136:139], v[80:95]
	ds_read_b128 v[168:171], v0 offset:224
	ds_read_b128 v[178:181], v0 offset:13024
	s_waitcnt lgkmcnt(4)
	v_mfma_f32_32x32x16_bf16 v[96:111], v[206:209], v[136:139], v[96:111]
	s_waitcnt lgkmcnt(3)
	v_mfma_f32_32x32x16_bf16 v[80:95], v[174:177], v[132:135], v[80:95]
	ds_read_b128 v[174:177], v0 offset:256
	ds_read_b128 v[206:209], v0 offset:13056
	s_waitcnt lgkmcnt(4)
	v_mfma_f32_32x32x16_bf16 v[96:111], v[210:213], v[132:135], v[96:111]
	s_waitcnt lgkmcnt(3)
	v_mfma_f32_32x32x16_bf16 v[80:95], v[168:171], v[128:131], v[80:95]
	ds_read_b128 v[168:171], v0 offset:288
	ds_read_b128 v[210:213], v0 offset:13088
	s_waitcnt lgkmcnt(4)
	v_mfma_f32_32x32x16_bf16 v[96:111], v[178:181], v[128:131], v[96:111]
	s_waitcnt lgkmcnt(3)
	v_mfma_f32_32x32x16_bf16 v[80:95], v[174:177], v[124:127], v[80:95]
	ds_read_b128 v[174:177], v0 offset:320
	ds_read_b128 v[178:181], v0 offset:13120
	s_waitcnt lgkmcnt(4)
	v_mfma_f32_32x32x16_bf16 v[96:111], v[206:209], v[124:127], v[96:111]
	s_waitcnt lgkmcnt(3)
	v_mfma_f32_32x32x16_bf16 v[80:95], v[168:171], v[120:123], v[80:95]
	ds_read_b128 v[168:171], v0 offset:352
	ds_read_b128 v[206:209], v0 offset:13152
	s_waitcnt lgkmcnt(4)
	v_mfma_f32_32x32x16_bf16 v[96:111], v[210:213], v[120:123], v[96:111]
	s_waitcnt lgkmcnt(3)
	v_mfma_f32_32x32x16_bf16 v[80:95], v[174:177], v[116:119], v[80:95]
	s_waitcnt lgkmcnt(2)
	v_mfma_f32_32x32x16_bf16 v[96:111], v[178:181], v[116:119], v[96:111]
	s_waitcnt vmcnt(5) lgkmcnt(1)
	v_mfma_f32_32x32x16_bf16 v[80:95], v[168:171], v[112:115], v[80:95]
	v_add_u32_e32 v0, s19, v188
	v_add_u32_e32 v173, v0, v191
	v_add_u32_e32 v15, 0x6000, v173
	v_add_u32_e32 v205, 0x7000, v173
	ds_read2_b64 v[168:171], v15 offset0:128 offset1:130
	ds_read2_b64 v[180:183], v205 offset0:160 offset1:162
	s_nop 5
	v_max_f32_e32 v0, v81, v81
	v_max_f32_e32 v14, v80, v80
	v_max_f32_e32 v0, v14, v0
	s_waitcnt lgkmcnt(2)
	v_mfma_f32_32x32x16_bf16 v[96:111], v[206:209], v[112:115], v[96:111]
	v_max3_f32 v0, v0, v82, v83
	v_max3_f32 v0, v0, v84, v85
	v_max3_f32 v0, v0, v86, v87
	v_max3_f32 v0, v0, v88, v89
	v_max3_f32 v0, v0, v90, v91
	v_max3_f32 v0, v0, v92, v93
	v_max3_f32 v0, v0, v94, v95
	s_nop 4
	v_max3_f32 v0, v0, v96, v97
	v_max3_f32 v0, v0, v98, v99
	v_max3_f32 v0, v0, v100, v101
	v_max3_f32 v0, v0, v102, v103
	v_max3_f32 v0, v0, v104, v105
	v_max3_f32 v0, v0, v106, v107
	v_max3_f32 v0, v0, v108, v109
	v_max3_f32 v0, v0, v110, v111
	ds_bpermute_b32 v14, v189, v0
	v_add_u32_e32 v206, 0x8000, v173
	v_add_u32_e32 v207, 0x9000, v173
	ds_read2_b64 v[176:179], v206 offset0:192 offset1:194
	s_waitcnt lgkmcnt(1)
	v_max3_f32 v14, v172, v0, v14
	v_mov_b32_e32 v236, v172
	v_sub_f32_e32 v0, v172, v14
	v_cmp_gt_f32_e32 vcc, 0xc1000000, v0
	v_exp_f32_e32 v0, v0
	ds_read2_b64 v[172:175], v207 offset0:224 offset1:226
	s_cbranch_vccz .Lthr_2_keep
	v_pk_mul_f32 v[78:79], v[78:79], v[0:1] op_sel_hi:[1,0]
	v_pk_mul_f32 v[76:77], v[76:77], v[0:1] op_sel_hi:[1,0]
	v_pk_mul_f32 v[74:75], v[74:75], v[0:1] op_sel_hi:[1,0]
	v_pk_mul_f32 v[72:73], v[72:73], v[0:1] op_sel_hi:[1,0]
	v_pk_mul_f32 v[70:71], v[70:71], v[0:1] op_sel_hi:[1,0]
	v_pk_mul_f32 v[68:69], v[68:69], v[0:1] op_sel_hi:[1,0]
	v_pk_mul_f32 v[66:67], v[66:67], v[0:1] op_sel_hi:[1,0]
	v_pk_mul_f32 v[64:65], v[64:65], v[0:1] op_sel_hi:[1,0]
	v_pk_mul_f32 v[62:63], v[62:63], v[0:1] op_sel_hi:[1,0]
	v_pk_mul_f32 v[60:61], v[60:61], v[0:1] op_sel_hi:[1,0]
	v_pk_mul_f32 v[58:59], v[58:59], v[0:1] op_sel_hi:[1,0]
	v_pk_mul_f32 v[56:57], v[56:57], v[0:1] op_sel_hi:[1,0]
	v_pk_mul_f32 v[54:55], v[54:55], v[0:1] op_sel_hi:[1,0]
	v_pk_mul_f32 v[52:53], v[52:53], v[0:1] op_sel_hi:[1,0]
	v_pk_mul_f32 v[50:51], v[50:51], v[0:1] op_sel_hi:[1,0]
	v_pk_mul_f32 v[48:49], v[48:49], v[0:1] op_sel_hi:[1,0]
	v_pk_mul_f32 v[46:47], v[46:47], v[0:1] op_sel_hi:[1,0]
	v_pk_mul_f32 v[44:45], v[44:45], v[0:1] op_sel_hi:[1,0]
	v_pk_mul_f32 v[42:43], v[42:43], v[0:1] op_sel_hi:[1,0]
	v_pk_mul_f32 v[40:41], v[40:41], v[0:1] op_sel_hi:[1,0]
	v_pk_mul_f32 v[38:39], v[38:39], v[0:1] op_sel_hi:[1,0]
	v_pk_mul_f32 v[36:37], v[36:37], v[0:1] op_sel_hi:[1,0]
	v_pk_mul_f32 v[34:35], v[34:35], v[0:1] op_sel_hi:[1,0]
	v_pk_mul_f32 v[32:33], v[32:33], v[0:1] op_sel_hi:[1,0]
	v_pk_mul_f32 v[30:31], v[30:31], v[0:1] op_sel_hi:[1,0]
	v_pk_mul_f32 v[28:29], v[28:29], v[0:1] op_sel_hi:[1,0]
	v_pk_mul_f32 v[26:27], v[26:27], v[0:1] op_sel_hi:[1,0]
	v_pk_mul_f32 v[24:25], v[24:25], v[0:1] op_sel_hi:[1,0]
	v_pk_mul_f32 v[22:23], v[22:23], v[0:1] op_sel_hi:[1,0]
	v_pk_mul_f32 v[20:21], v[20:21], v[0:1] op_sel_hi:[1,0]
	v_pk_mul_f32 v[18:19], v[18:19], v[0:1] op_sel_hi:[1,0]
	v_pk_mul_f32 v[16:17], v[16:17], v[0:1] op_sel_hi:[1,0]

; #define A_LOAD(kt) do { const size_t ko = (size_t)(kt) * 64; st0 = *(const u32x4*)(kn_src + ko * 2048); st1 = *(const u32x4*)(kn_src + (ko + 32) * 2048); \
;         st2 = *(const u32x4*)(kr_src + ko * 64); st3 = *(const u32x4*)(v_src + ko); st4 = *(const u32x4*)(v_src + ko + (size_t)64 * 8192); } while (0)
; DI void attn_unit(LAS unsigned char* lds, int wid, int b, int h, int qb) {
;     ...
;         if (kt + 1 < nkt) A_LOAD(kt + 1);
;     ...
;         if (kt + 1 < nkt) A_WRITE(buf ^ 1);
.LBB0_1096:
	s_add_u32 s70, s70, 0x40000
	s_addc_u32 s71, s71, 0
	s_add_u32 s72, s72, 0x40000
	s_addc_u32 s73, s73, 0
	s_add_u32 s78, s78, 0x2000
	s_addc_u32 s79, s79, 0
	s_add_u32 s74, s74, 0x80
	s_addc_u32 s75, s75, 0
	s_add_u32 s76, s76, 0x80
	s_addc_u32 s77, s77, 0
	s_xor_b32 s18, s18, 1
	s_mul_i32 s18, s18, 0xa800
	s_add_i32 s18, s18, 0
	v_add_u32_e32 v0, s18, v190
	s_waitcnt vmcnt(4)
	ds_write_b128 v0, v[2:5]
	s_waitcnt vmcnt(3)
	ds_write_b128 v0, v[6:9] offset:12800
	v_add_u32_e32 v0, s18, v192
	s_add_i32 s57, s57, 1
	s_waitcnt vmcnt(2)
	ds_write_b128 v0, v[10:13] offset:256
	v_add_u32_e32 v0, s18, v203
	v_add_u32_e32 v2, 0x6400, v0
	v_add_u32_e32 v0, 0x8600, v0


; DI void attn_unit(LAS unsigned char* lds, int wid, int b, int h, int qb) {
;     ...
;     for (int kt = 0; kt < nkt; ++kt) {
	s_cmp_eq_u32 s4, s57

; DI void attn_unit(LAS unsigned char* lds, int wid, int b, int h, int qb) {
;     ...
;         if (kt + 1 < nkt) A_WRITE(buf ^ 1);
;         __syncthreads();
	s_waitcnt vmcnt(1)
	ds_write2_b64 v2, v[160:161], v[162:163] offset1:1
	s_waitcnt vmcnt(0)
	ds_write2_b64 v0, v[164:165], v[166:167] offset1:1
	s_waitcnt lgkmcnt(0)
	s_barrier
	s_cbranch_scc1 .LBB0_1098
	v_mov_b32_e32 v172, v14
	s_branch .LBB0_1091
